# chunk mixer epilogue: per-head bias/gain loads hoisted ahead of the next tile loads, one counted vmcnt wait instead of a drain per 16x16 block
# speedup vs baseline: 1.0019x; 1.0019x over previous
.LBB0_382:
	s_waitcnt lgkmcnt(0)
	s_waitcnt lgkmcnt(0)
	s_barrier
	ds_read_b128 v[62:65], v202 offset:34816
	ds_read_b128 v[34:37], v202 offset:39168
	ds_read_b128 v[48:51], v201
	ds_read_b128 v[204:207], v201 offset:64
	ds_read_b128 v[58:61], v202 offset:34880
	s_waitcnt lgkmcnt(2)
	v_mfma_f32_16x16x32_bf16 v[172:175], v[62:65], v[48:51], 0
	ds_read_b128 v[208:211], v201 offset:4352
	ds_read_b128 v[212:215], v201 offset:4416
	ds_read_b128 v[38:41], v202 offset:39232
	v_lshl_add_u64 v[180:181], s[62:63], 0, v[158:159]
	v_add_co_u32_e32 v184, vcc, s30, v180
	v_mfma_f32_16x16x32_bf16 v[216:219], v[34:37], v[48:51], 0
	ds_read_b128 v[50:53], v202 offset:34944
	ds_read_b128 v[220:223], v201 offset:128
	ds_read_b128 v[224:227], v201 offset:192
	ds_read_b128 v[54:57], v202 offset:35008
	s_waitcnt vmcnt(21)
	v_lshlrev_b32_e32 v48, 16, v42
	s_waitcnt lgkmcnt(7)
	v_mfma_f32_16x16x32_bf16 v[172:175], v[58:61], v[204:207], v[172:175]
	v_and_b32_e32 v49, 0xffff0000, v42
	v_lshlrev_b32_e32 v42, 16, v43
	v_and_b32_e32 v43, 0xffff0000, v43
	s_waitcnt lgkmcnt(2)
	v_mfma_f32_16x16x32_bf16 v[172:175], v[50:53], v[220:223], v[172:175]
	v_addc_co_u32_e32 v185, vcc, 0, v181, vcc
	s_waitcnt vmcnt(20)
	v_lshlrev_b32_e32 v188, 16, v178
	s_waitcnt lgkmcnt(0)
	v_mfma_f32_16x16x32_bf16 v[172:175], v[54:57], v[224:227], v[172:175]
	v_and_b32_e32 v189, 0xffff0000, v178
	s_add_u32 s22, s22, 0x200
	s_addc_u32 s23, s23, 0
	v_mfma_f32_16x16x32_bf16 v[204:207], v[38:41], v[204:207], v[216:219]
	v_lshl_add_u64 v[136:137], v[136:137], 0, s[14:15]
	v_lshl_add_u64 v[138:139], v[138:139], 0, s[14:15]
	v_lshl_add_u64 v[140:141], v[140:141], 0, s[14:15]
	v_mfma_f32_16x16x32_bf16 v[228:231], v[62:65], v[208:211], 0
	v_lshl_add_u64 v[134:135], v[134:135], 0, s[14:15]
	v_lshl_add_u64 v[116:117], v[116:117], 0, s[16:17]
	v_lshl_add_u64 v[118:119], v[118:119], 0, s[16:17]
	v_mfma_f32_16x16x32_bf16 v[208:211], v[34:37], v[208:211], 0
	v_lshl_add_u64 v[120:121], v[120:121], 0, s[16:17]
	v_lshl_add_u64 v[150:151], v[150:151], 0, s[14:15]
	v_lshl_add_u64 v[152:153], v[152:153], 0, s[14:15]
	v_mfma_f32_16x16x32_bf16 v[228:231], v[58:61], v[212:215], v[228:231]
	v_lshl_add_u64 v[154:155], v[154:155], 0, s[14:15]
	v_lshl_add_u64 v[156:157], v[156:157], 0, s[14:15]
	s_cmpk_eq_i32 s22, 0x800
	v_mfma_f32_16x16x32_bf16 v[208:211], v[38:41], v[212:215], v[208:211]
	v_lshl_add_u64 v[158:159], v[158:159], 0, s[14:15]
	s_waitcnt vmcnt(8)
	v_pk_add_f32 v[172:173], v[172:173], v[66:67] op_sel_hi:[1,0]
	v_pk_add_f32 v[180:181], v[174:175], v[66:67] op_sel_hi:[1,0]
	v_pk_mul_f32 v[174:175], v[172:173], v[48:49]
	v_pk_mul_f32 v[172:173], v[180:181], v[42:43]
	s_nop 0
	v_pk_mul_f32 v[42:43], v[244:245], v[174:175]
	v_pk_mul_f32 v[44:45], v[246:247], v[172:173]
	v_cvt_pk_bf16_f32 v42, v42, v43
	v_cvt_pk_bf16_f32 v43, v44, v45
	global_store_dwordx2 v[184:185], v[42:43], off
	ds_read_b128 v[46:49], v202 offset:39296
	ds_read_b128 v[42:45], v202 offset:39360
	ds_read_b128 v[216:219], v201 offset:8704
	s_waitcnt lgkmcnt(2)
	v_mfma_f32_16x16x32_bf16 v[204:207], v[46:49], v[220:223], v[204:207]
	v_lshlrev_b32_e32 v220, 16, v179
	v_and_b32_e32 v221, 0xffff0000, v179
	s_waitcnt lgkmcnt(1)
	v_mfma_f32_16x16x32_bf16 v[178:181], v[42:45], v[224:227], v[204:207]
	s_nop 7
	v_pk_add_f32 v[178:179], v[178:179], v[66:67] op_sel_hi:[1,0]
	v_pk_add_f32 v[204:205], v[180:181], v[66:67] op_sel_hi:[1,0]
	v_pk_mul_f32 v[180:181], v[178:179], v[188:189]
	v_pk_mul_f32 v[178:179], v[204:205], v[220:221]
	s_waitcnt lgkmcnt(0)
	v_mfma_f32_16x16x32_bf16 v[220:223], v[62:65], v[216:219], 0
	s_nop 0
	v_pk_mul_f32 v[188:189], v[180:181], v[248:249]
	v_pk_mul_f32 v[204:205], v[178:179], v[250:251]
	v_cvt_pk_bf16_f32 v188, v188, v189
	v_cvt_pk_bf16_f32 v189, v204, v205
	global_store_dwordx2 v[184:185], v[188:189], off offset:32
	v_mov_b32_e32 v66, v240
	ds_read_b128 v[204:207], v201 offset:8768
	ds_read_b128 v[232:235], v201 offset:4480
	ds_read_b128 v[236:239], v201 offset:4544
	s_waitcnt lgkmcnt(1)
	v_mfma_f32_16x16x32_bf16 v[212:215], v[50:53], v[232:235], v[228:231]
	v_lshl_add_u64 v[188:189], s[62:63], 0, v[148:149]
	s_nop 1
	v_add_co_u32_e32 v228, vcc, s30, v188
	s_waitcnt lgkmcnt(0)
	v_mfma_f32_16x16x32_bf16 v[212:215], v[54:57], v[236:239], v[212:215]
	v_lshlrev_b32_e32 v184, 16, v176
	v_and_b32_e32 v185, 0xffff0000, v176
	v_lshlrev_b32_e32 v176, 16, v177
	v_and_b32_e32 v177, 0xffff0000, v177
	v_addc_co_u32_e32 v229, vcc, 0, v189, vcc
	v_mfma_f32_16x16x32_bf16 v[208:211], v[46:49], v[232:235], v[208:211]
	v_lshl_add_u64 v[230:231], s[62:63], 0, v[146:147]
	v_lshl_add_u64 v[146:147], v[146:147], 0, s[14:15]
	v_lshl_add_u64 v[148:149], v[148:149], 0, s[14:15]
	v_mfma_f32_16x16x32_bf16 v[208:211], v[42:45], v[236:239], v[208:211]
	s_nop 0
	v_pk_add_f32 v[188:189], v[212:213], v[66:67] op_sel_hi:[1,0]
	v_pk_add_f32 v[212:213], v[214:215], v[66:67] op_sel_hi:[1,0]
	v_pk_mul_f32 v[184:185], v[188:189], v[184:185]
	v_pk_mul_f32 v[176:177], v[212:213], v[176:177]
	s_nop 0
	v_pk_mul_f32 v[188:189], v[244:245], v[184:185]
	v_pk_mul_f32 v[212:213], v[246:247], v[176:177]
	v_cvt_pk_bf16_f32 v188, v188, v189
	v_cvt_pk_bf16_f32 v189, v212, v213
	global_store_dwordx2 v[228:229], v[188:189], off
	v_lshlrev_b32_e32 v188, 16, v170
	v_and_b32_e32 v189, 0xffff0000, v170
	v_lshlrev_b32_e32 v170, 16, v171
	v_and_b32_e32 v171, 0xffff0000, v171
	v_pk_add_f32 v[208:209], v[208:209], v[66:67] op_sel_hi:[1,0]
	v_pk_add_f32 v[210:211], v[210:211], v[66:67] op_sel_hi:[1,0]
	v_pk_mul_f32 v[188:189], v[208:209], v[188:189]
	v_pk_mul_f32 v[170:171], v[210:211], v[170:171]
	s_nop 0
	v_pk_mul_f32 v[208:209], v[188:189], v[248:249]
	v_pk_mul_f32 v[210:211], v[170:171], v[250:251]
	v_cvt_pk_bf16_f32 v208, v208, v209
	v_cvt_pk_bf16_f32 v209, v210, v211
	global_store_dwordx2 v[228:229], v[208:209], off offset:32
	v_mov_b32_e32 v66, v241
	v_mfma_f32_16x16x32_bf16 v[208:211], v[34:37], v[216:219], 0
	v_lshlrev_b32_e32 v228, 16, v168
	v_and_b32_e32 v229, 0xffff0000, v168
	v_lshlrev_b32_e32 v168, 16, v169
	v_mfma_f32_16x16x32_bf16 v[216:219], v[58:61], v[204:207], v[220:223]
	s_nop 2
	ds_read_b128 v[220:223], v201 offset:8832
	ds_read_b128 v[224:227], v201 offset:8896
	v_and_b32_e32 v169, 0xffff0000, v169
	v_mfma_f32_16x16x32_bf16 v[204:207], v[38:41], v[204:207], v[208:211]
	s_waitcnt lgkmcnt(1)
	v_mfma_f32_16x16x32_bf16 v[208:211], v[50:53], v[220:223], v[216:219]
	s_waitcnt lgkmcnt(0)
	v_mfma_f32_16x16x32_bf16 v[208:211], v[54:57], v[224:227], v[208:211]
	s_nop 0
	v_add_co_u32_e32 v216, vcc, s30, v230
	s_nop 1
	v_addc_co_u32_e32 v217, vcc, 0, v231, vcc
	v_mfma_f32_16x16x32_bf16 v[204:207], v[46:49], v[220:223], v[204:207]
	s_nop 0
	s_nop 0
	v_pk_add_f32 v[208:209], v[208:209], v[66:67] op_sel_hi:[1,0]
	v_pk_add_f32 v[210:211], v[210:211], v[66:67] op_sel_hi:[1,0]
	v_pk_mul_f32 v[228:229], v[208:209], v[228:229]
	v_pk_mul_f32 v[230:231], v[210:211], v[168:169]
	s_nop 0
	v_pk_mul_f32 v[168:169], v[244:245], v[228:229]
	v_pk_mul_f32 v[208:209], v[246:247], v[230:231]
	v_cvt_pk_bf16_f32 v168, v168, v169
	v_cvt_pk_bf16_f32 v169, v208, v209
	global_store_dwordx2 v[216:217], v[168:169], off
	v_lshlrev_b32_e32 v212, 16, v166
	v_and_b32_e32 v213, 0xffff0000, v166
	v_lshlrev_b32_e32 v214, 16, v167
	v_and_b32_e32 v215, 0xffff0000, v167
	v_mfma_f32_16x16x32_bf16 v[166:169], v[42:45], v[224:227], v[204:207]
	s_nop 7
	v_pk_add_f32 v[166:167], v[166:167], v[66:67] op_sel_hi:[1,0]
	v_pk_add_f32 v[168:169], v[168:169], v[66:67] op_sel_hi:[1,0]
	v_pk_mul_f32 v[220:221], v[166:167], v[212:213]
	v_pk_mul_f32 v[222:223], v[168:169], v[214:215]
	s_nop 0
	v_pk_mul_f32 v[166:167], v[220:221], v[248:249]
	v_pk_mul_f32 v[168:169], v[222:223], v[250:251]
	v_cvt_pk_bf16_f32 v166, v166, v167
	v_cvt_pk_bf16_f32 v167, v168, v169
	global_store_dwordx2 v[216:217], v[166:167], off offset:32
	v_mov_b32_e32 v66, v242
	s_nop 0
	ds_read_b128 v[204:207], v201 offset:13056
	ds_read_b128 v[208:211], v201 offset:13120
	s_waitcnt lgkmcnt(1)
	v_mfma_f32_16x16x32_bf16 v[62:65], v[62:65], v[204:207], 0
	ds_read_b128 v[212:215], v201 offset:13184
	ds_read_b128 v[216:219], v201 offset:13248
	v_lshlrev_b32_e32 v186, 16, v164
	v_and_b32_e32 v187, 0xffff0000, v164
	s_waitcnt lgkmcnt(2)
	v_mfma_f32_16x16x32_bf16 v[58:61], v[58:61], v[208:211], v[62:65]
	s_waitcnt lgkmcnt(1)
	v_mfma_f32_16x16x32_bf16 v[50:53], v[50:53], v[212:215], v[58:61]
	s_nop 0
	v_lshlrev_b32_e32 v62, 16, v165
	v_and_b32_e32 v63, 0xffff0000, v165
	v_lshl_add_u64 v[64:65], s[62:63], 0, v[142:143]
	s_waitcnt lgkmcnt(0)
	v_mfma_f32_16x16x32_bf16 v[50:53], v[54:57], v[216:219], v[50:53]
	v_add_co_u32_e32 v58, vcc, s30, v64
	v_lshlrev_b32_e32 v60, 16, v162
	s_nop 0
	v_addc_co_u32_e32 v59, vcc, 0, v65, vcc
	v_mfma_f32_16x16x32_bf16 v[34:37], v[34:37], v[204:207], 0
	v_and_b32_e32 v61, 0xffff0000, v162
	v_lshl_add_u64 v[142:143], v[142:143], 0, s[14:15]
	s_nop 0
	v_pk_add_f32 v[50:51], v[50:51], v[66:67] op_sel_hi:[1,0]
	v_pk_add_f32 v[52:53], v[52:53], v[66:67] op_sel_hi:[1,0]
	v_pk_mul_f32 v[54:55], v[50:51], v[186:187]
	v_pk_mul_f32 v[56:57], v[52:53], v[62:63]
	s_nop 0
	v_pk_mul_f32 v[50:51], v[244:245], v[54:55]
	v_pk_mul_f32 v[52:53], v[246:247], v[56:57]
	v_cvt_pk_bf16_f32 v50, v50, v51
	v_cvt_pk_bf16_f32 v51, v52, v53
	global_store_dwordx2 v[58:59], v[50:51], off
	v_mfma_f32_16x16x32_bf16 v[34:37], v[38:41], v[208:211], v[34:37]
	v_mov_b32_e32 v39, v174
	v_mov_b32_e32 v41, v172
	v_mov_b32_e32 v174, v185
	v_mfma_f32_16x16x32_bf16 v[34:37], v[46:49], v[212:215], v[34:37]
	v_mov_b32_e32 v172, v177
	v_mov_b32_e32 v38, v184
	v_mov_b32_e32 v40, v176
	v_mfma_f32_16x16x32_bf16 v[34:37], v[42:45], v[216:219], v[34:37]
	v_mov_b32_e32 v43, v180
	v_mov_b32_e32 v45, v178
	v_mov_b32_e32 v180, v189
	v_mov_b32_e32 v178, v171
	v_pk_mul_f32 v[46:47], v[174:175], v[174:175]
	v_pk_mul_f32 v[48:49], v[172:173], v[172:173]
	v_lshlrev_b32_e32 v62, 16, v163
	v_and_b32_e32 v63, 0xffff0000, v163
	v_mov_b32_e32 v42, v188
	v_mov_b32_e32 v44, v170
	v_pk_mul_f32 v[64:65], v[180:181], v[180:181]
	v_pk_mul_f32 v[162:163], v[178:179], v[178:179]
	v_pk_fma_f32 v[38:39], v[38:39], v[38:39], v[46:47]
	v_pk_fma_f32 v[40:41], v[40:41], v[40:41], v[48:49]
	v_pk_fma_f32 v[42:43], v[42:43], v[42:43], v[64:65]
	v_pk_fma_f32 v[44:45], v[44:45], v[44:45], v[162:163]
	v_pk_add_f32 v[38:39], v[38:39], v[40:41]
	v_pk_add_f32 v[40:41], v[42:43], v[44:45]
	v_pk_add_f32 v[38:39], v[160:161], v[38:39]
	v_pk_add_f32 v[34:35], v[34:35], v[66:67] op_sel_hi:[1,0]
	v_pk_add_f32 v[36:37], v[36:37], v[66:67] op_sel_hi:[1,0]
	v_pk_add_f32 v[160:161], v[40:41], v[38:39]
	v_mov_b32_e32 v39, v228
	v_mov_b32_e32 v41, v230
	v_pk_mul_f32 v[34:35], v[34:35], v[60:61]
	v_pk_mul_f32 v[36:37], v[36:37], v[62:63]
	v_mov_b32_e32 v228, v55
	v_mov_b32_e32 v230, v57
	v_mov_b32_e32 v43, v220
	v_mov_b32_e32 v45, v222
	v_mov_b32_e32 v38, v54
	v_mov_b32_e32 v40, v56
	v_mov_b32_e32 v220, v35
	v_mov_b32_e32 v222, v37
	v_pk_mul_f32 v[46:47], v[228:229], v[228:229]
	v_pk_mul_f32 v[48:49], v[230:231], v[230:231]
	v_mov_b32_e32 v42, v34
	v_mov_b32_e32 v44, v36
	v_pk_mul_f32 v[54:55], v[220:221], v[220:221]
	v_pk_mul_f32 v[56:57], v[222:223], v[222:223]
	v_pk_fma_f32 v[38:39], v[38:39], v[38:39], v[46:47]
	v_pk_fma_f32 v[40:41], v[40:41], v[40:41], v[48:49]
	v_pk_fma_f32 v[42:43], v[42:43], v[42:43], v[54:55]
	v_pk_fma_f32 v[44:45], v[44:45], v[44:45], v[56:57]
	v_pk_add_f32 v[38:39], v[38:39], v[40:41]
	v_pk_add_f32 v[40:41], v[42:43], v[44:45]
	v_pk_add_f32 v[38:39], v[132:133], v[38:39]
	s_nop 0
	v_pk_mul_f32 v[34:35], v[34:35], v[248:249]
	v_pk_mul_f32 v[36:37], v[36:37], v[250:251]
	v_pk_add_f32 v[132:133], v[40:41], v[38:39]
	v_cvt_pk_bf16_f32 v34, v34, v35
	v_cvt_pk_bf16_f32 v35, v36, v37
	global_store_dwordx2 v[58:59], v[34:35], off offset:32
	s_barrier
	s_cbranch_scc1 .LBB0_385
.LBB0_383:
	v_lshl_add_u64 v[38:39], v[124:125], 0, s[22:23]
	global_load_dwordx4 v[34:37], v[38:39], off offset:-16
	s_nop 0
	global_load_dwordx4 v[38:41], v[38:39], off
	v_lshl_add_u64 v[42:43], v[126:127], 0, s[22:23]
	global_load_dwordx4 v[44:47], v[42:43], off offset:-16
	global_load_dwordx4 v[48:51], v[42:43], off
	s_waitcnt vmcnt(11)
	ds_write_b128 v198, v[2:5]
	s_waitcnt vmcnt(10)
	ds_write_b128 v199, v[6:9]
	s_waitcnt vmcnt(9)
	ds_write_b128 v198, v[10:13] offset:17408
	s_waitcnt vmcnt(8)
	ds_write_b128 v200, v[14:17]
	v_lshl_add_u64 v[42:43], v[128:129], 0, s[22:23]
	global_load_dwordx4 v[52:55], v[42:43], off
	global_load_dwordx4 v[56:59], v[42:43], off offset:-16
	v_lshl_add_u64 v[162:163], v[130:131], 0, s[22:23]
	ds_read_b32 v66, v77
	global_load_dwordx4 v[60:63], v[162:163], off
	global_load_dwordx4 v[172:175], v[162:163], off offset:-16
	v_lshl_add_u64 v[164:165], s[62:63], 0, v[150:151]
	v_add_co_u32_e32 v162, vcc, s29, v164
	v_lshl_add_u64 v[166:167], s[62:63], 0, v[152:153]
	s_nop 0
	v_addc_co_u32_e32 v163, vcc, 0, v165, vcc
	v_add_co_u32_e32 v164, vcc, s29, v166
	v_lshl_add_u64 v[168:169], s[62:63], 0, v[154:155]
	s_nop 0
	v_addc_co_u32_e32 v165, vcc, 0, v167, vcc
	v_add_co_u32_e32 v166, vcc, s29, v168
	v_lshl_add_u64 v[204:205], s[62:63], 0, v[156:157]
	s_nop 0
	v_addc_co_u32_e32 v167, vcc, 0, v169, vcc
	global_load_dwordx2 v[42:43], v[162:163], off
	global_load_dwordx2 v[178:179], v[162:163], off offset:32
	global_load_dwordx2 v[176:177], v[164:165], off
	global_load_dwordx2 v[170:171], v[164:165], off offset:32
	v_add_co_u32_e32 v162, vcc, 0x8800000, v204
	s_waitcnt vmcnt(15)
	v_lshlrev_b32_e32 v64, 16, v18
	v_addc_co_u32_e32 v163, vcc, 0, v205, vcc
	global_load_dwordx2 v[168:169], v[166:167], off
	s_nop 0
	global_load_dwordx2 v[166:167], v[166:167], off offset:32
	s_nop 0
	global_load_dwordx2 v[164:165], v[162:163], off
	s_nop 0
	global_load_dwordx2 v[162:163], v[162:163], off offset:32
	v_and_b32_e32 v65, 0xffff0000, v18
	v_lshlrev_b32_e32 v180, 16, v19
	v_and_b32_e32 v181, 0xffff0000, v19
	v_lshlrev_b32_e32 v182, 16, v20
	v_and_b32_e32 v183, 0xffff0000, v20
	v_lshlrev_b32_e32 v184, 16, v21
	v_and_b32_e32 v185, 0xffff0000, v21
	s_waitcnt vmcnt(18)
	v_lshlrev_b32_e32 v186, 16, v22
	v_and_b32_e32 v187, 0xffff0000, v22
	s_waitcnt lgkmcnt(0)
	v_pk_mul_f32 v[64:65], v[66:67], v[64:65] op_sel_hi:[0,1]
	v_pk_mul_f32 v[180:181], v[66:67], v[180:181] op_sel_hi:[0,1]
	v_pk_mul_f32 v[182:183], v[66:67], v[182:183] op_sel_hi:[0,1]
	v_pk_mul_f32 v[184:185], v[66:67], v[184:185] op_sel_hi:[0,1]
	v_pk_mul_f32 v[186:187], v[66:67], v[186:187] op_sel_hi:[0,1]
	v_lshlrev_b32_e32 v188, 16, v23
	v_and_b32_e32 v189, 0xffff0000, v23
	s_cmpk_eq_i32 s22, 0x600
	s_waitcnt vmcnt(15)
	v_pk_mul_f32 v[34:35], v[64:65], v[34:35]
	v_pk_mul_f32 v[36:37], v[180:181], v[36:37]
	s_waitcnt vmcnt(14)
	v_pk_mul_f32 v[38:39], v[182:183], v[38:39]
	v_pk_mul_f32 v[40:41], v[184:185], v[40:41]
	s_waitcnt vmcnt(13)
	v_pk_mul_f32 v[44:45], v[186:187], v[44:45]
	v_cvt_pk_bf16_f32 v34, v34, v35
	v_cvt_pk_bf16_f32 v35, v36, v37
	v_cvt_pk_bf16_f32 v36, v38, v39
	v_cvt_pk_bf16_f32 v37, v40, v41
	v_cvt_pk_bf16_f32 v38, v44, v45
	ds_write_b16 v81, v34 offset:34816
	ds_write_b16_d16_hi v81, v34 offset:35088
	ds_write_b16 v81, v35 offset:35360
	ds_write_b16_d16_hi v81, v35 offset:35632
	ds_write_b16 v81, v36 offset:35904
	ds_write_b16_d16_hi v81, v36 offset:36176
	ds_write_b16 v81, v37 offset:36448
	ds_write_b16_d16_hi v81, v37 offset:36720
	ds_write_b16 v87, v38 offset:34816
	ds_write_b16_d16_hi v87, v38 offset:35088
	v_pk_mul_f32 v[34:35], v[66:67], v[188:189] op_sel_hi:[0,1]
	v_pk_mul_f32 v[34:35], v[34:35], v[46:47]
	s_nop 0
	v_cvt_pk_bf16_f32 v34, v34, v35
	ds_write_b16 v87, v34 offset:35360
	ds_write_b16_d16_hi v87, v34 offset:35632
	v_lshlrev_b32_e32 v34, 16, v24
	v_and_b32_e32 v35, 0xffff0000, v24
	v_pk_mul_f32 v[34:35], v[66:67], v[34:35] op_sel_hi:[0,1]
	s_waitcnt vmcnt(12)
	v_pk_mul_f32 v[34:35], v[34:35], v[48:49]
	s_nop 0
	v_cvt_pk_bf16_f32 v34, v34, v35
	ds_write_b16 v87, v34 offset:35904
	ds_write_b16_d16_hi v87, v34 offset:36176
	v_lshlrev_b32_e32 v34, 16, v25
	v_and_b32_e32 v35, 0xffff0000, v25
	v_pk_mul_f32 v[34:35], v[66:67], v[34:35] op_sel_hi:[0,1]
	v_pk_mul_f32 v[34:35], v[34:35], v[50:51]
	s_nop 0
	v_cvt_pk_bf16_f32 v34, v34, v35
	ds_write_b16 v87, v34 offset:36448
	ds_write_b16_d16_hi v87, v34 offset:36720
	v_lshlrev_b32_e32 v34, 16, v26
	v_and_b32_e32 v35, 0xffff0000, v26
	v_pk_mul_f32 v[34:35], v[66:67], v[34:35] op_sel_hi:[0,1]
	s_waitcnt vmcnt(10)
	v_pk_mul_f32 v[34:35], v[34:35], v[56:57]
	s_nop 0
	v_cvt_pk_bf16_f32 v34, v34, v35
	ds_write_b16 v99, v34 offset:34816
	ds_write_b16_d16_hi v99, v34 offset:35088
	v_lshlrev_b32_e32 v34, 16, v27
	v_and_b32_e32 v35, 0xffff0000, v27
	v_pk_mul_f32 v[34:35], v[66:67], v[34:35] op_sel_hi:[0,1]
	v_pk_mul_f32 v[34:35], v[34:35], v[58:59]
	s_nop 0
	v_cvt_pk_bf16_f32 v34, v34, v35
	ds_write_b16 v99, v34 offset:35360
	ds_write_b16_d16_hi v99, v34 offset:35632
	v_lshlrev_b32_e32 v34, 16, v28
	v_and_b32_e32 v35, 0xffff0000, v28
	v_pk_mul_f32 v[34:35], v[66:67], v[34:35] op_sel_hi:[0,1]
	v_pk_mul_f32 v[34:35], v[34:35], v[52:53]
	s_nop 0
	v_cvt_pk_bf16_f32 v34, v34, v35
	ds_write_b16 v99, v34 offset:35904
	ds_write_b16_d16_hi v99, v34 offset:36176
	v_lshlrev_b32_e32 v34, 16, v29
	v_and_b32_e32 v35, 0xffff0000, v29
	v_pk_mul_f32 v[34:35], v[66:67], v[34:35] op_sel_hi:[0,1]
	v_pk_mul_f32 v[34:35], v[34:35], v[54:55]
	s_nop 0
	v_cvt_pk_bf16_f32 v34, v34, v35
	ds_write_b16 v99, v34 offset:36448
	ds_write_b16_d16_hi v99, v34 offset:36720
	v_lshlrev_b32_e32 v34, 16, v30
	v_and_b32_e32 v35, 0xffff0000, v30
	v_pk_mul_f32 v[34:35], v[66:67], v[34:35] op_sel_hi:[0,1]
	s_waitcnt vmcnt(8)
	v_pk_mul_f32 v[34:35], v[34:35], v[172:173]
	s_nop 0
	v_cvt_pk_bf16_f32 v34, v34, v35
	ds_write_b16 v193, v34 offset:34816
	ds_write_b16_d16_hi v193, v34 offset:35088
	v_lshlrev_b32_e32 v34, 16, v31
	v_and_b32_e32 v35, 0xffff0000, v31
	v_pk_mul_f32 v[34:35], v[66:67], v[34:35] op_sel_hi:[0,1]
	v_pk_mul_f32 v[34:35], v[34:35], v[174:175]
	s_nop 0
	v_cvt_pk_bf16_f32 v34, v34, v35
	ds_write_b16 v193, v34 offset:35360
	ds_write_b16_d16_hi v193, v34 offset:35632
	v_lshlrev_b32_e32 v34, 16, v32
	v_and_b32_e32 v35, 0xffff0000, v32
	v_pk_mul_f32 v[34:35], v[66:67], v[34:35] op_sel_hi:[0,1]
	v_pk_mul_f32 v[34:35], v[34:35], v[60:61]
	s_nop 0
	v_cvt_pk_bf16_f32 v34, v34, v35
	ds_write_b16 v193, v34 offset:35904
	ds_write_b16_d16_hi v193, v34 offset:36176
	v_lshlrev_b32_e32 v34, 16, v33
	v_and_b32_e32 v35, 0xffff0000, v33
	v_pk_mul_f32 v[34:35], v[66:67], v[34:35] op_sel_hi:[0,1]
	v_pk_mul_f32 v[34:35], v[34:35], v[62:63]
	s_nop 0
	v_cvt_pk_bf16_f32 v34, v34, v35
	ds_write_b16 v193, v34 offset:36448
	ds_write_b16_d16_hi v193, v34 offset:36720
	v_lshl_add_u64 v[186:187], v[144:145], 0, s[22:23]
	v_lshl_add_u64 v[182:183], v[122:123], 0, s[22:23]
	global_load_dwordx4 v[244:247], v[182:183], off offset:-64
	global_load_dwordx4 v[248:251], v[182:183], off
	global_load_dword v66, v[186:187], off
	global_load_dword v240, v[186:187], off offset:64
	global_load_dword v241, v[186:187], off offset:128
	global_load_dword v242, v[186:187], off offset:192
	s_cbranch_scc1 .Lch_last_head
	v_lshl_add_u64 v[10:11], s[62:63], 0, v[116:117]
	v_add_co_u32_e32 v2, vcc, 0x708000, v10
	v_lshl_add_u64 v[18:19], s[20:21], 0, v[134:135]
	s_nop 0
	v_addc_co_u32_e32 v3, vcc, 0, v11, vcc
	v_add_co_u32_e32 v10, vcc, 0x70c000, v10
	v_lshl_add_u64 v[20:21], s[20:21], 0, v[140:141]
	s_nop 0
	v_addc_co_u32_e32 v11, vcc, 0, v11, vcc
	v_add_co_u32_e32 v18, vcc, 0xf8001000, v18
	v_lshl_add_u64 v[26:27], s[20:21], 0, v[138:139]
	s_nop 0
	v_addc_co_u32_e32 v19, vcc, -1, v19, vcc
	v_add_co_u32_e32 v22, vcc, 0xf8001000, v20
	v_lshl_add_u64 v[28:29], s[20:21], 0, v[136:137]
	s_nop 0
	v_addc_co_u32_e32 v23, vcc, -1, v21, vcc
	v_add_co_u32_e32 v26, vcc, 0xf8001000, v26
	v_lshl_add_u64 v[6:7], s[62:63], 0, v[118:119]
	s_nop 0
	v_addc_co_u32_e32 v27, vcc, -1, v27, vcc
	v_add_co_u32_e32 v30, vcc, 0xf8001000, v28
	v_lshl_add_u64 v[14:15], s[62:63], 0, v[120:121]
	s_nop 0
	v_addc_co_u32_e32 v31, vcc, -1, v29, vcc
	global_load_dwordx4 v[2:5], v[2:3], off
	s_nop 0
	global_load_dwordx4 v[6:9], v[6:7], off
	s_nop 0
	global_load_dwordx4 v[10:13], v[10:11], off
	s_nop 0
	global_load_dwordx4 v[14:17], v[14:15], off
	s_nop 0
	global_load_dwordx4 v[18:21], v[18:19], off offset:-1824
	s_nop 0
	global_load_dwordx4 v[22:25], v[22:23], off offset:-1824
	s_nop 0
	global_load_dwordx4 v[26:29], v[26:27], off offset:-1824
	s_nop 0
	global_load_dwordx4 v[30:33], v[30:31], off offset:-1824
	s_branch .LBB0_382
.Lch_last_head:
	global_load_dword v252, v[186:187], off
	global_load_dword v252, v[186:187], off
	global_load_dword v252, v[186:187], off
	global_load_dword v252, v[186:187], off
	global_load_dword v252, v[186:187], off
	global_load_dword v252, v[186:187], off
	global_load_dword v252, v[186:187], off
	global_load_dword v252, v[186:187], off
	s_branch .LBB0_382
